# v11 plus row-max reduction split into two interleaved independent v_max3 chains (half the dependency depth) in all six attention V bodies
# speedup vs baseline: 1.0226x; 1.0041x over previous
; __device__ __forceinline__ float max3f(float a, float b, float c) { return __builtin_fmaxf(__builtin_fmaxf(a, b), c); }
; __device__ __forceinline__ void rowmax_adjust(f32x16& p0, f32x16& p1, float& m2, f32x16& negm, float& alpha, const bool first) {
;     constexpr float THR2 = THR * 1.4426950408889634f;
;     float pmax = max3f(p0[0], p0[1], p0[2]);
; #pragma unroll
;     for (int r = 3; r < 15; r += 2) pmax = max3f(pmax, p0[r], p0[r + 1]);
;     pmax = max3f(pmax, p0[15], p1[0]);
; #pragma unroll
;     for (int r = 1; r < 15; r += 2) pmax = max3f(pmax, p1[r], p1[r + 1]);
;     pmax = fmaxf(pmax, p1[15]);
;     { auto rr = __builtin_amdgcn_permlane32_swap(__float_as_uint(pmax), __float_as_uint(pmax), false, false);
;       pmax = fmaxf(__uint_as_float(rr[0]), __uint_as_float(rr[1])); }
;     if (!first && __builtin_expect(__all(pmax <= THR2), 1)) { alpha = 1.f; }
;     else {
;         const float delta = first ? pmax : fmaxf(pmax, 0.f);
;         alpha = first ? 1.f : __builtin_amdgcn_exp2f(-delta);
.Ld1_a_nopv:
	s_waitcnt lgkmcnt(0)
	s_mov_b64 s[0:1], s[72:73]
	s_barrier
	v_max3_f32 v168, v96, v97, v98
	v_max3_f32 v169, v81, v82, v83
	v_max3_f32 v168, v168, v99, v100
	v_max3_f32 v169, v169, v84, v85
	v_max3_f32 v168, v168, v101, v102
	v_max3_f32 v169, v169, v86, v87
	v_max3_f32 v168, v168, v103, v104
	v_max3_f32 v169, v169, v88, v89
	v_max3_f32 v168, v168, v105, v106
	v_max3_f32 v169, v169, v90, v91
	v_max3_f32 v168, v168, v107, v108
	v_max3_f32 v169, v169, v92, v93
	v_max3_f32 v168, v168, v109, v110
	v_max3_f32 v169, v169, v94, v95
	v_max3_f32 v168, v168, v111, v80
	v_max_f32_e32 v168, v168, v169
	v_mov_b32_e32 v169, v168
	s_nop 1
	v_permlane32_swap_b32_e32 v168, v169
	v_max_f32_e32 v168, v168, v169
	v_cmp_ge_f32_e32 vcc, s83, v168
	v_mov_b32_e32 v184, 1.0
	s_cmp_lg_u64 s[0:1], 0
	s_cbranch_scc1 .Lvt0_first
	s_cmp_lg_u64 vcc, exec
	s_cbranch_scc1 .Lvt0_rare
	s_branch .LBB0_1162

; __device__ __forceinline__ float max3f(float a, float b, float c) { return __builtin_fmaxf(__builtin_fmaxf(a, b), c); }
; __device__ __forceinline__ void rowmax_adjust(f32x16& p0, f32x16& p1, float& m2, f32x16& negm, float& alpha, const bool first) {
;     ...
;     float pmax = max3f(p0[0], p0[1], p0[2]);
; #pragma unroll
;     for (int r = 3; r < 15; r += 2) pmax = max3f(pmax, p0[r], p0[r + 1]);
;     pmax = max3f(pmax, p0[15], p1[0]);
; #pragma unroll
;     for (int r = 1; r < 15; r += 2) pmax = max3f(pmax, p1[r], p1[r + 1]);
;     pmax = fmaxf(pmax, p1[15]);
;     { auto rr = __builtin_amdgcn_permlane32_swap(__float_as_uint(pmax), __float_as_uint(pmax), false, false);
;       pmax = fmaxf(__uint_as_float(rr[0]), __uint_as_float(rr[1])); }
;     if (!first && __builtin_expect(__all(pmax <= THR2), 1)) { alpha = 1.f; }
.LBB0_1164:
	s_min_u32 s0, s95, 0x7f
	s_lshl_b32 s0, s0, 16
	s_add_i32 s16, s0, 0x40000
	s_add_u32 s0, s58, s16
	s_addc_u32 s1, s59, 0
	v_lshl_add_u64 v[80:81], s[0:1], 0, v[200:201]
	v_lshl_add_u64 v[82:83], s[0:1], 0, v[202:203]
	global_load_dwordx4 v[132:135], v[80:81], off
	global_load_dwordx4 v[128:131], v[82:83], off
	v_lshl_add_u64 v[80:81], v[204:205], 0, s[16:17]
	global_load_dwordx4 v[136:139], v[80:81], off
	s_waitcnt lgkmcnt(0)
	s_barrier
	s_or_b32 s0, s95, 1
	s_and_b32 s1, s0, 0xff
	s_mulk_i32 s1, 0xab
	s_bfe_u32 s1, s1, 0x70009
	s_mul_i32 s1, s1, 3
	s_sub_i32 s0, s0, s1
	s_and_b32 s0, s0, 0xff
	s_mulk_i32 s0, 0x2400
	v_add_u32_e32 v84, s0, v218
	s_and_b32 s0, s51, 0x8000
	v_add_u32_e32 v187, s0, v217
	ds_read_b128 v[80:83], v84
	ds_read_b128 v[192:195], v84 offset:4608
	ds_read_b128 v[188:191], v84 offset:32
	ds_read_b128 v[196:199], v84 offset:4640
	ds_read_b128 v[220:223], v84 offset:64
	ds_read_b128 v[228:231], v84 offset:4672
	ds_read_b128 v[224:227], v84 offset:96
	ds_read_b128 v[232:235], v84 offset:4704
	ds_read_b64_tr_b16 v[164:165], v187 offset:0
	ds_read_b64_tr_b16 v[166:167], v187 offset:0x800
	ds_read_b64_tr_b16 v[160:161], v187 offset:0x1000
	ds_read_b64_tr_b16 v[162:163], v187 offset:0x1800
	ds_read_b64_tr_b16 v[156:157], v187 offset:0x2000
	ds_read_b64_tr_b16 v[158:159], v187 offset:0x2800
	ds_read_b64_tr_b16 v[152:153], v187 offset:0x3000
	ds_read_b64_tr_b16 v[154:155], v187 offset:0x3800
	s_waitcnt lgkmcnt(15)
	v_mfma_f32_32x32x16_bf16 v[96:111], v[80:83], v[112:115], v[64:79]
	s_waitcnt lgkmcnt(14)
	v_mfma_f32_32x32x16_bf16 v[80:95], v[192:195], v[112:115], v[64:79]
	s_waitcnt lgkmcnt(13)
	v_mfma_f32_32x32x16_bf16 v[96:111], v[188:191], v[116:119], v[96:111]
	s_waitcnt lgkmcnt(12)
	v_mfma_f32_32x32x16_bf16 v[80:95], v[196:199], v[116:119], v[80:95]
	s_waitcnt lgkmcnt(8)
	ds_read_b64_tr_b16 v[188:189], v187 offset:0x200
	ds_read_b64_tr_b16 v[190:191], v187 offset:0xa00
	ds_read_b64_tr_b16 v[192:193], v187 offset:0x1200
	ds_read_b64_tr_b16 v[194:195], v187 offset:0x1a00
	ds_read_b64_tr_b16 v[196:197], v187 offset:0x2200
	ds_read_b64_tr_b16 v[198:199], v187 offset:0x2a00
	ds_read_b64_tr_b16 v[236:237], v187 offset:0x3200
	ds_read_b64_tr_b16 v[238:239], v187 offset:0x3a00
	v_mfma_f32_32x32x16_bf16 v[96:111], v[220:223], v[120:123], v[96:111]
	v_mfma_f32_32x32x16_bf16 v[80:95], v[228:231], v[120:123], v[80:95]
	v_mfma_f32_32x32x16_bf16 v[96:111], v[224:227], v[124:127], v[96:111]
	v_mfma_f32_32x32x16_bf16 v[80:95], v[232:235], v[124:127], v[80:95]
	ds_read_b64_tr_b16 v[220:221], v187 offset:0x600
	ds_read_b64_tr_b16 v[222:223], v187 offset:0xe00
	ds_read_b64_tr_b16 v[224:225], v187 offset:0x1600
	ds_read_b64_tr_b16 v[226:227], v187 offset:0x1e00
	ds_read_b64_tr_b16 v[228:229], v187 offset:0x2600
	ds_read_b64_tr_b16 v[230:231], v187 offset:0x2e00
	ds_read_b64_tr_b16 v[232:233], v187 offset:0x3600
	ds_read_b64_tr_b16 v[234:235], v187 offset:0x3e00
	s_waitcnt lgkmcnt(15)
	v_mfma_f32_32x32x16_bf16 v[48:63], v[180:183], v[164:167], v[48:63]
	v_mfma_f32_32x32x16_bf16 v[48:63], v[176:179], v[160:163], v[48:63]
	v_mfma_f32_32x32x16_bf16 v[48:63], v[172:175], v[156:159], v[48:63]
	v_mfma_f32_32x32x16_bf16 v[48:63], v[168:171], v[152:155], v[48:63]
	ds_read_b64_tr_b16 v[164:165], v187 offset:0x400
	ds_read_b64_tr_b16 v[166:167], v187 offset:0xc00
	ds_read_b64_tr_b16 v[160:161], v187 offset:0x1400
	ds_read_b64_tr_b16 v[162:163], v187 offset:0x1c00
	ds_read_b64_tr_b16 v[156:157], v187 offset:0x2400
	ds_read_b64_tr_b16 v[158:159], v187 offset:0x2c00
	ds_read_b64_tr_b16 v[152:153], v187 offset:0x3400
	ds_read_b64_tr_b16 v[154:155], v187 offset:0x3c00
	s_waitcnt lgkmcnt(15)
	v_mfma_f32_32x32x16_bf16 v[32:47], v[180:183], v[188:191], v[32:47]
	v_mfma_f32_32x32x16_bf16 v[32:47], v[176:179], v[192:195], v[32:47]
	v_mfma_f32_32x32x16_bf16 v[32:47], v[172:175], v[196:199], v[32:47]
	v_mfma_f32_32x32x16_bf16 v[32:47], v[168:171], v[236:239], v[32:47]
	s_waitcnt lgkmcnt(8)
	v_mfma_f32_32x32x16_bf16 v[0:15], v[180:183], v[220:223], v[0:15]
	v_mfma_f32_32x32x16_bf16 v[0:15], v[176:179], v[224:227], v[0:15]
	v_mfma_f32_32x32x16_bf16 v[0:15], v[172:175], v[228:231], v[0:15]
	v_mfma_f32_32x32x16_bf16 v[0:15], v[168:171], v[232:235], v[0:15]
	s_waitcnt lgkmcnt(0)
	v_mfma_f32_32x32x16_bf16 v[16:31], v[180:183], v[164:167], v[16:31]
	v_mfma_f32_32x32x16_bf16 v[16:31], v[176:179], v[160:163], v[16:31]
	v_mfma_f32_32x32x16_bf16 v[16:31], v[172:175], v[156:159], v[16:31]
	v_mfma_f32_32x32x16_bf16 v[16:31], v[168:171], v[152:155], v[16:31]
	s_barrier
	v_max3_f32 v168, v96, v97, v98
	v_max3_f32 v169, v81, v82, v83
	v_max3_f32 v168, v168, v99, v100
	v_max3_f32 v169, v169, v84, v85
	v_max3_f32 v168, v168, v101, v102
	v_max3_f32 v169, v169, v86, v87
	v_max3_f32 v168, v168, v103, v104
	v_max3_f32 v169, v169, v88, v89
	v_max3_f32 v168, v168, v105, v106
	v_max3_f32 v169, v169, v90, v91
	v_max3_f32 v168, v168, v107, v108
	v_max3_f32 v169, v169, v92, v93
	v_max3_f32 v168, v168, v109, v110
	v_max3_f32 v169, v169, v94, v95
	v_max3_f32 v168, v168, v111, v80
	v_max_f32_e32 v168, v168, v169
	v_mov_b32_e32 v169, v168
	s_nop 1
	v_permlane32_swap_b32_e32 v168, v169
	v_max_f32_e32 v168, v168, v169
	v_cmp_ge_f32_e32 vcc, s83, v168
	v_mov_b32_e32 v187, 1.0
	s_cmp_eq_u64 vcc, exec
	s_cbranch_scc1 .LBB0_1169
	s_branch .LBB0_1171

; __device__ __forceinline__ float max3f(float a, float b, float c) { return __builtin_fmaxf(__builtin_fmaxf(a, b), c); }
; __device__ __forceinline__ void rowmax_adjust(f32x16& p0, f32x16& p1, float& m2, f32x16& negm, float& alpha, const bool first) {
;     constexpr float THR2 = THR * 1.4426950408889634f;
;     float pmax = max3f(p0[0], p0[1], p0[2]);
; #pragma unroll
;     for (int r = 3; r < 15; r += 2) pmax = max3f(pmax, p0[r], p0[r + 1]);
;     pmax = max3f(pmax, p0[15], p1[0]);
; #pragma unroll
;     for (int r = 1; r < 15; r += 2) pmax = max3f(pmax, p1[r], p1[r + 1]);
;     pmax = fmaxf(pmax, p1[15]);
;     { auto rr = __builtin_amdgcn_permlane32_swap(__float_as_uint(pmax), __float_as_uint(pmax), false, false);
;       pmax = fmaxf(__uint_as_float(rr[0]), __uint_as_float(rr[1])); }
;     if (!first && __builtin_expect(__all(pmax <= THR2), 1)) { alpha = 1.f; }
.Ld1_b_nopv:
	s_waitcnt lgkmcnt(0)
	s_mov_b64 s[0:1], s[60:61]
	s_barrier
	v_max3_f32 v168, v96, v97, v98
	v_max3_f32 v169, v81, v82, v83
	v_max3_f32 v168, v168, v99, v100
	v_max3_f32 v169, v169, v84, v85
	v_max3_f32 v168, v168, v101, v102
	v_max3_f32 v169, v169, v86, v87
	v_max3_f32 v168, v168, v103, v104
	v_max3_f32 v169, v169, v88, v89
	v_max3_f32 v168, v168, v105, v106
	v_max3_f32 v169, v169, v90, v91
	v_max3_f32 v168, v168, v107, v108
	v_max3_f32 v169, v169, v92, v93
	v_max3_f32 v168, v168, v109, v110
	v_max3_f32 v169, v169, v94, v95
	v_max3_f32 v168, v168, v111, v80
	v_max_f32_e32 v168, v168, v169
	v_mov_b32_e32 v169, v168
	s_nop 1
	v_permlane32_swap_b32_e32 v168, v169
	v_max_f32_e32 v168, v168, v169
	v_cmp_ge_f32_e32 vcc, s83, v168
	v_mov_b32_e32 v184, 1.0
	s_cmp_lg_u64 s[0:1], 0
	s_cbranch_scc1 .Lvt31_first
	s_cmp_lg_u64 vcc, exec
	s_cbranch_scc1 .Lvt31_rare
	s_branch .LBB0_1193

; __device__ __forceinline__ float max3f(float a, float b, float c) { return __builtin_fmaxf(__builtin_fmaxf(a, b), c); }
; __device__ __forceinline__ void rowmax_adjust(f32x16& p0, f32x16& p1, float& m2, f32x16& negm, float& alpha, const bool first) {
;     ...
;     float pmax = max3f(p0[0], p0[1], p0[2]);
; #pragma unroll
;     for (int r = 3; r < 15; r += 2) pmax = max3f(pmax, p0[r], p0[r + 1]);
;     pmax = max3f(pmax, p0[15], p1[0]);
; #pragma unroll
;     for (int r = 1; r < 15; r += 2) pmax = max3f(pmax, p1[r], p1[r + 1]);
;     pmax = fmaxf(pmax, p1[15]);
;     { auto rr = __builtin_amdgcn_permlane32_swap(__float_as_uint(pmax), __float_as_uint(pmax), false, false);
;       pmax = fmaxf(__uint_as_float(rr[0]), __uint_as_float(rr[1])); }
;     if (!first && __builtin_expect(__all(pmax <= THR2), 1)) { alpha = 1.f; }
.LBB0_1195:
	s_min_u32 s0, s64, 0x7f
	s_lshl_b32 s0, s0, 16
	s_add_i32 s16, s0, 0x40000
	s_add_u32 s0, s58, s16
	s_addc_u32 s1, s59, 0
	v_lshl_add_u64 v[80:81], s[0:1], 0, v[200:201]
	v_lshl_add_u64 v[82:83], s[0:1], 0, v[202:203]
	global_load_dwordx4 v[132:135], v[80:81], off
	global_load_dwordx4 v[128:131], v[82:83], off
	v_lshl_add_u64 v[80:81], v[204:205], 0, s[16:17]
	global_load_dwordx4 v[136:139], v[80:81], off
	s_waitcnt lgkmcnt(0)
	s_barrier
	s_or_b32 s0, s64, 1
	s_and_b32 s1, s0, 0xff
	s_mulk_i32 s1, 0xab
	s_bfe_u32 s1, s1, 0x70009
	s_mul_i32 s1, s1, 3
	s_sub_i32 s0, s0, s1
	s_and_b32 s0, s0, 0xff
	s_mulk_i32 s0, 0x2400
	v_add_u32_e32 v84, s0, v218
	s_and_b32 s0, s51, 0x8000
	v_add_u32_e32 v187, s0, v217
	ds_read_b128 v[80:83], v84
	ds_read_b128 v[192:195], v84 offset:4608
	ds_read_b128 v[188:191], v84 offset:32
	ds_read_b128 v[196:199], v84 offset:4640
	ds_read_b128 v[220:223], v84 offset:64
	ds_read_b128 v[228:231], v84 offset:4672
	ds_read_b128 v[224:227], v84 offset:96
	ds_read_b128 v[232:235], v84 offset:4704
	ds_read_b64_tr_b16 v[164:165], v187 offset:0
	ds_read_b64_tr_b16 v[166:167], v187 offset:0x800
	ds_read_b64_tr_b16 v[160:161], v187 offset:0x1000
	ds_read_b64_tr_b16 v[162:163], v187 offset:0x1800
	ds_read_b64_tr_b16 v[156:157], v187 offset:0x2000
	ds_read_b64_tr_b16 v[158:159], v187 offset:0x2800
	ds_read_b64_tr_b16 v[152:153], v187 offset:0x3000
	ds_read_b64_tr_b16 v[154:155], v187 offset:0x3800
	s_waitcnt lgkmcnt(15)
	v_mfma_f32_32x32x16_bf16 v[96:111], v[80:83], v[112:115], v[64:79]
	s_waitcnt lgkmcnt(14)
	v_mfma_f32_32x32x16_bf16 v[80:95], v[192:195], v[112:115], v[64:79]
	s_waitcnt lgkmcnt(13)
	v_mfma_f32_32x32x16_bf16 v[96:111], v[188:191], v[116:119], v[96:111]
	s_waitcnt lgkmcnt(12)
	v_mfma_f32_32x32x16_bf16 v[80:95], v[196:199], v[116:119], v[80:95]
	s_waitcnt lgkmcnt(8)
	ds_read_b64_tr_b16 v[188:189], v187 offset:0x200
	ds_read_b64_tr_b16 v[190:191], v187 offset:0xa00
	ds_read_b64_tr_b16 v[192:193], v187 offset:0x1200
	ds_read_b64_tr_b16 v[194:195], v187 offset:0x1a00
	ds_read_b64_tr_b16 v[196:197], v187 offset:0x2200
	ds_read_b64_tr_b16 v[198:199], v187 offset:0x2a00
	ds_read_b64_tr_b16 v[236:237], v187 offset:0x3200
	ds_read_b64_tr_b16 v[238:239], v187 offset:0x3a00
	v_mfma_f32_32x32x16_bf16 v[96:111], v[220:223], v[120:123], v[96:111]
	v_mfma_f32_32x32x16_bf16 v[80:95], v[228:231], v[120:123], v[80:95]
	v_mfma_f32_32x32x16_bf16 v[96:111], v[224:227], v[124:127], v[96:111]
	v_mfma_f32_32x32x16_bf16 v[80:95], v[232:235], v[124:127], v[80:95]
	ds_read_b64_tr_b16 v[220:221], v187 offset:0x600
	ds_read_b64_tr_b16 v[222:223], v187 offset:0xe00
	ds_read_b64_tr_b16 v[224:225], v187 offset:0x1600
	ds_read_b64_tr_b16 v[226:227], v187 offset:0x1e00
	ds_read_b64_tr_b16 v[228:229], v187 offset:0x2600
	ds_read_b64_tr_b16 v[230:231], v187 offset:0x2e00
	ds_read_b64_tr_b16 v[232:233], v187 offset:0x3600
	ds_read_b64_tr_b16 v[234:235], v187 offset:0x3e00
	s_waitcnt lgkmcnt(15)
	v_mfma_f32_32x32x16_bf16 v[48:63], v[180:183], v[164:167], v[48:63]
	v_mfma_f32_32x32x16_bf16 v[48:63], v[176:179], v[160:163], v[48:63]
	v_mfma_f32_32x32x16_bf16 v[48:63], v[172:175], v[156:159], v[48:63]
	v_mfma_f32_32x32x16_bf16 v[48:63], v[168:171], v[152:155], v[48:63]
	ds_read_b64_tr_b16 v[164:165], v187 offset:0x400
	ds_read_b64_tr_b16 v[166:167], v187 offset:0xc00
	ds_read_b64_tr_b16 v[160:161], v187 offset:0x1400
	ds_read_b64_tr_b16 v[162:163], v187 offset:0x1c00
	ds_read_b64_tr_b16 v[156:157], v187 offset:0x2400
	ds_read_b64_tr_b16 v[158:159], v187 offset:0x2c00
	ds_read_b64_tr_b16 v[152:153], v187 offset:0x3400
	ds_read_b64_tr_b16 v[154:155], v187 offset:0x3c00
	s_waitcnt lgkmcnt(15)
	v_mfma_f32_32x32x16_bf16 v[32:47], v[180:183], v[188:191], v[32:47]
	v_mfma_f32_32x32x16_bf16 v[32:47], v[176:179], v[192:195], v[32:47]
	v_mfma_f32_32x32x16_bf16 v[32:47], v[172:175], v[196:199], v[32:47]
	v_mfma_f32_32x32x16_bf16 v[32:47], v[168:171], v[236:239], v[32:47]
	s_waitcnt lgkmcnt(8)
	v_mfma_f32_32x32x16_bf16 v[0:15], v[180:183], v[220:223], v[0:15]
	v_mfma_f32_32x32x16_bf16 v[0:15], v[176:179], v[224:227], v[0:15]
	v_mfma_f32_32x32x16_bf16 v[0:15], v[172:175], v[228:231], v[0:15]
	v_mfma_f32_32x32x16_bf16 v[0:15], v[168:171], v[232:235], v[0:15]
	s_waitcnt lgkmcnt(0)
	v_mfma_f32_32x32x16_bf16 v[16:31], v[180:183], v[164:167], v[16:31]
	v_mfma_f32_32x32x16_bf16 v[16:31], v[176:179], v[160:163], v[16:31]
	v_mfma_f32_32x32x16_bf16 v[16:31], v[172:175], v[156:159], v[16:31]
	v_mfma_f32_32x32x16_bf16 v[16:31], v[168:171], v[152:155], v[16:31]
	s_barrier
	v_max3_f32 v168, v96, v97, v98
	v_max3_f32 v169, v81, v82, v83
	v_max3_f32 v168, v168, v99, v100
	v_max3_f32 v169, v169, v84, v85
	v_max3_f32 v168, v168, v101, v102
	v_max3_f32 v169, v169, v86, v87
	v_max3_f32 v168, v168, v103, v104
	v_max3_f32 v169, v169, v88, v89
	v_max3_f32 v168, v168, v105, v106
	v_max3_f32 v169, v169, v90, v91
	v_max3_f32 v168, v168, v107, v108
	v_max3_f32 v169, v169, v92, v93
	v_max3_f32 v168, v168, v109, v110
	v_max3_f32 v169, v169, v94, v95
	v_max3_f32 v168, v168, v111, v80
	v_max_f32_e32 v168, v168, v169
	v_mov_b32_e32 v169, v168
	s_nop 1
	v_permlane32_swap_b32_e32 v168, v169
	v_max_f32_e32 v168, v168, v169
	v_cmp_ge_f32_e32 vcc, s83, v168
	v_mov_b32_e32 v187, 1.0
	s_cmp_eq_u64 vcc, exec
	s_cbranch_scc1 .LBB0_1200
	s_branch .LBB0_1202

; __device__ __forceinline__ float max3f(float a, float b, float c) { return __builtin_fmaxf(__builtin_fmaxf(a, b), c); }
; __device__ __forceinline__ void rowmax_adjust(f32x16& p0, f32x16& p1, float& m2, f32x16& negm, float& alpha, const bool first) {
;     ...
;     float pmax = max3f(p0[0], p0[1], p0[2]);
; #pragma unroll
;     for (int r = 3; r < 15; r += 2) pmax = max3f(pmax, p0[r], p0[r + 1]);
;     pmax = max3f(pmax, p0[15], p1[0]);
; #pragma unroll
;     for (int r = 1; r < 15; r += 2) pmax = max3f(pmax, p1[r], p1[r + 1]);
;     pmax = fmaxf(pmax, p1[15]);
;     { auto rr = __builtin_amdgcn_permlane32_swap(__float_as_uint(pmax), __float_as_uint(pmax), false, false);
;       pmax = fmaxf(__uint_as_float(rr[0]), __uint_as_float(rr[1])); }
;     if (!first && __builtin_expect(__all(pmax <= THR2), 1)) { alpha = 1.f; }
.LBB0_1228:
	s_add_i32 s61, s51, -3
	s_mul_i32 s10, s61, 0xab
	s_bfe_u32 s10, s10, 0x70009
	s_mul_i32 s10, s10, 3
	s_sub_i32 s10, s61, s10
	s_and_b32 s10, s10, 0xff
	s_mulk_i32 s10, 0x4400
	v_add_u32_e32 v52, s10, v152
	ds_read_b128 v[48:51], v52 offset:32768
	ds_read_b128 v[158:161], v52 offset:32800
	ds_read_b128 v[162:165], v52 offset:41472
	ds_read_b128 v[166:169], v52 offset:41504
	ds_read_b128 v[170:173], v52 offset:32832
	ds_read_b128 v[174:177], v52 offset:32864
	ds_read_b128 v[178:181], v52 offset:41536
	ds_read_b128 v[182:185], v52 offset:41568
	ds_read_b128 v[186:189], v52 offset:32896
	ds_read_b128 v[190:193], v52 offset:32928
	ds_read_b128 v[194:197], v52 offset:41600
	ds_read_b128 v[202:205], v52 offset:41632
	s_waitcnt lgkmcnt(11)
	v_mfma_f32_32x32x16_bf16 v[64:79], v[48:51], v[80:83], v[32:47]
	s_waitcnt lgkmcnt(9)
	v_mfma_f32_32x32x16_bf16 v[48:63], v[162:165], v[80:83], v[32:47]
	v_mfma_f32_32x32x16_bf16 v[64:79], v[158:161], v[84:87], v[64:79]
	s_waitcnt lgkmcnt(8)
	v_mfma_f32_32x32x16_bf16 v[48:63], v[166:169], v[84:87], v[48:63]
	s_waitcnt lgkmcnt(7)
	v_mfma_f32_32x32x16_bf16 v[64:79], v[170:173], v[88:91], v[64:79]
	s_waitcnt lgkmcnt(5)
	v_mfma_f32_32x32x16_bf16 v[48:63], v[178:181], v[88:91], v[48:63]
	s_waitcnt lgkmcnt(4)
	s_waitcnt lgkmcnt(3)
	s_waitcnt lgkmcnt(1)
	s_waitcnt lgkmcnt(0)
	s_and_b32 s62, s60, 0x6000
	v_add_u32_e32 v198, s62, v155
	ds_read_b64_tr_b16 v[158:159], v198 offset:0
	ds_read_b64_tr_b16 v[160:161], v198 offset:0x400
	ds_read_b64_tr_b16 v[162:163], v198 offset:0x800
	ds_read_b64_tr_b16 v[164:165], v198 offset:0xc00
	ds_read_b64_tr_b16 v[166:167], v198 offset:0x1000
	ds_read_b64_tr_b16 v[168:169], v198 offset:0x1400
	ds_read_b64_tr_b16 v[170:171], v198 offset:0x1800
	ds_read_b64_tr_b16 v[172:173], v198 offset:0x1c00
	ds_read_b64_tr_b16 v[178:179], v198 offset:0x200
	ds_read_b64_tr_b16 v[180:181], v198 offset:0x600
	ds_read_b64_tr_b16 v[210:211], v198 offset:0xa00
	ds_read_b64_tr_b16 v[212:213], v198 offset:0xe00
	ds_read_b64_tr_b16 v[214:215], v198 offset:0x1200
	ds_read_b64_tr_b16 v[216:217], v198 offset:0x1600
	ds_read_b64_tr_b16 v[218:219], v198 offset:0x1a00
	ds_read_b64_tr_b16 v[220:221], v198 offset:0x1e00
	s_nop 0
	v_mfma_f32_32x32x16_bf16 v[64:79], v[174:177], v[92:95], v[64:79]
	v_mfma_f32_32x32x16_bf16 v[48:63], v[182:185], v[92:95], v[48:63]
	v_mfma_f32_32x32x16_bf16 v[64:79], v[186:189], v[96:99], v[64:79]
	v_mfma_f32_32x32x16_bf16 v[48:63], v[194:197], v[96:99], v[48:63]
	v_mfma_f32_32x32x16_bf16 v[64:79], v[190:193], v[100:103], v[64:79]
	v_mfma_f32_32x32x16_bf16 v[48:63], v[202:205], v[100:103], v[48:63]
	s_waitcnt lgkmcnt(0)
	v_mfma_f32_32x32x16_bf16 v[0:15], v[140:143], v[158:161], v[0:15]
	v_mfma_f32_32x32x16_bf16 v[16:31], v[140:143], v[178:181], v[16:31]
	v_mfma_f32_32x32x16_bf16 v[0:15], v[136:139], v[162:165], v[0:15]
	v_mfma_f32_32x32x16_bf16 v[16:31], v[136:139], v[210:213], v[16:31]
	v_mfma_f32_32x32x16_bf16 v[0:15], v[132:135], v[166:169], v[0:15]
	v_mfma_f32_32x32x16_bf16 v[16:31], v[132:135], v[214:217], v[16:31]
	v_mfma_f32_32x32x16_bf16 v[0:15], v[128:131], v[170:173], v[0:15]
	v_mfma_f32_32x32x16_bf16 v[16:31], v[128:131], v[218:221], v[16:31]
	s_barrier
	s_nop 1
	v_max3_f32 v128, v64, v65, v66
	v_max3_f32 v129, v49, v50, v51
	v_max3_f32 v128, v128, v67, v68
	v_max3_f32 v129, v129, v52, v53
	v_max3_f32 v128, v128, v69, v70
	v_max3_f32 v129, v129, v54, v55
	v_max3_f32 v128, v128, v71, v72
	v_max3_f32 v129, v129, v56, v57
	v_max3_f32 v128, v128, v73, v74
	v_max3_f32 v129, v129, v58, v59
	v_max3_f32 v128, v128, v75, v76
	v_max3_f32 v129, v129, v60, v61
	v_max3_f32 v128, v128, v77, v78
	v_max3_f32 v129, v129, v62, v63
	v_max3_f32 v128, v128, v79, v48
	v_max_f32_e32 v128, v128, v129
	v_mov_b32_e32 v129, v128
	s_nop 1
	v_permlane32_swap_b32_e32 v128, v129
	v_max_f32_e32 v128, v128, v129
	v_cmp_ge_f32_e32 vcc, s83, v128
	v_mov_b32_e32 v158, 1.0
	s_cmp_eq_u64 vcc, exec
	s_cbranch_scc1 .LBB0_1233
	s_branch .LBB0_1244

; __device__ __forceinline__ float max3f(float a, float b, float c) { return __builtin_fmaxf(__builtin_fmaxf(a, b), c); }
; __device__ __forceinline__ void rowmax_adjust(f32x16& p0, f32x16& p1, float& m2, f32x16& negm, float& alpha, const bool first) {
;     ...
;     float pmax = max3f(p0[0], p0[1], p0[2]);
; #pragma unroll
;     for (int r = 3; r < 15; r += 2) pmax = max3f(pmax, p0[r], p0[r + 1]);
;     pmax = max3f(pmax, p0[15], p1[0]);
; #pragma unroll
;     for (int r = 1; r < 15; r += 2) pmax = max3f(pmax, p1[r], p1[r + 1]);
;     pmax = fmaxf(pmax, p1[15]);
;     { auto rr = __builtin_amdgcn_permlane32_swap(__float_as_uint(pmax), __float_as_uint(pmax), false, false);
;       pmax = fmaxf(__uint_as_float(rr[0]), __uint_as_float(rr[1])); }
;     if (!first && __builtin_expect(__all(pmax <= THR2), 1)) { alpha = 1.f; }
.LBB0_1236:
	s_min_u32 s10, s61, 0x7f
	s_lshl_b32 s10, s10, 6
	s_add_i32 s16, s10, 0x100
	s_add_i32 s38, s60, 0xffffa000
	s_mul_i32 s10, s16, 0x600
	s_add_u32 s10, s58, s10
	s_addc_u32 s11, s59, 0
	s_lshl_b32 s16, s16, 10
	v_lshl_add_u64 v[48:49], v[148:149], 0, s[16:17]
	v_lshl_add_u64 v[50:51], s[10:11], 0, v[146:147]
	global_load_dwordx4 v[112:115], v[48:49], off
	global_load_dwordx4 v[108:111], v[50:51], off
	v_lshl_add_u64 v[48:49], s[10:11], 0, v[200:201]
	global_load_dwordx4 v[104:107], v[48:49], off
	s_waitcnt lgkmcnt(0)
	s_barrier
	s_or_b32 s10, s61, 1
	s_and_b32 s11, s10, 0xff
	s_mulk_i32 s11, 0xab
	s_bfe_u32 s11, s11, 0x70009
	s_mul_i32 s11, s11, 3
	s_sub_i32 s10, s10, s11
	s_and_b32 s10, s10, 0xff
	s_mulk_i32 s10, 0x4400
	v_add_u32_e32 v52, s10, v152
	ds_read_b128 v[48:51], v52 offset:32768
	ds_read_b128 v[162:165], v52 offset:32800
	ds_read_b128 v[166:169], v52 offset:41472
	ds_read_b128 v[170:173], v52 offset:41504
	ds_read_b128 v[174:177], v52 offset:32832
	ds_read_b128 v[178:181], v52 offset:32864
	ds_read_b128 v[182:185], v52 offset:41536
	ds_read_b128 v[186:189], v52 offset:41568
	ds_read_b128 v[190:193], v52 offset:32896
	ds_read_b128 v[194:197], v52 offset:32928
	ds_read_b128 v[202:205], v52 offset:41600
	ds_read_b128 v[210:213], v52 offset:41632
	s_and_b32 s10, s38, 0x4000
	s_waitcnt lgkmcnt(11)
	v_mfma_f32_32x32x16_bf16 v[64:79], v[48:51], v[80:83], v[32:47]
	s_waitcnt lgkmcnt(9)
	v_mfma_f32_32x32x16_bf16 v[48:63], v[166:169], v[80:83], v[32:47]
	v_mfma_f32_32x32x16_bf16 v[64:79], v[162:165], v[84:87], v[64:79]
	s_waitcnt lgkmcnt(8)
	v_mfma_f32_32x32x16_bf16 v[48:63], v[170:173], v[84:87], v[48:63]
	s_waitcnt lgkmcnt(7)
	v_mfma_f32_32x32x16_bf16 v[64:79], v[174:177], v[88:91], v[64:79]
	s_waitcnt lgkmcnt(5)
	v_mfma_f32_32x32x16_bf16 v[48:63], v[182:185], v[88:91], v[48:63]
	v_add_u32_e32 v161, s10, v155
	s_waitcnt lgkmcnt(4)
	s_waitcnt lgkmcnt(3)
	s_waitcnt lgkmcnt(1)
	s_waitcnt lgkmcnt(0)
	ds_read_b64_tr_b16 v[162:163], v161 offset:0
	ds_read_b64_tr_b16 v[164:165], v161 offset:0x400
	ds_read_b64_tr_b16 v[166:167], v161 offset:0x800
	ds_read_b64_tr_b16 v[168:169], v161 offset:0xc00
	ds_read_b64_tr_b16 v[170:171], v161 offset:0x1000
	ds_read_b64_tr_b16 v[172:173], v161 offset:0x1400
	ds_read_b64_tr_b16 v[174:175], v161 offset:0x1800
	ds_read_b64_tr_b16 v[176:177], v161 offset:0x1c00
	ds_read_b64_tr_b16 v[182:183], v161 offset:0x200
	ds_read_b64_tr_b16 v[184:185], v161 offset:0x600
	ds_read_b64_tr_b16 v[214:215], v161 offset:0xa00
	ds_read_b64_tr_b16 v[216:217], v161 offset:0xe00
	ds_read_b64_tr_b16 v[218:219], v161 offset:0x1200
	ds_read_b64_tr_b16 v[220:221], v161 offset:0x1600
	ds_read_b64_tr_b16 v[222:223], v161 offset:0x1a00
	ds_read_b64_tr_b16 v[224:225], v161 offset:0x1e00
	s_nop 0
	v_mfma_f32_32x32x16_bf16 v[64:79], v[178:181], v[92:95], v[64:79]
	v_mfma_f32_32x32x16_bf16 v[48:63], v[186:189], v[92:95], v[48:63]
	v_mfma_f32_32x32x16_bf16 v[64:79], v[190:193], v[96:99], v[64:79]
	v_mfma_f32_32x32x16_bf16 v[48:63], v[202:205], v[96:99], v[48:63]
	v_mfma_f32_32x32x16_bf16 v[64:79], v[194:197], v[100:103], v[64:79]
	v_mfma_f32_32x32x16_bf16 v[48:63], v[210:213], v[100:103], v[48:63]
	s_waitcnt lgkmcnt(0)
	v_mfma_f32_32x32x16_bf16 v[0:15], v[140:143], v[162:165], v[0:15]
	v_mfma_f32_32x32x16_bf16 v[16:31], v[140:143], v[182:185], v[16:31]
	v_mfma_f32_32x32x16_bf16 v[0:15], v[136:139], v[166:169], v[0:15]
	v_mfma_f32_32x32x16_bf16 v[16:31], v[136:139], v[214:217], v[16:31]
	v_mfma_f32_32x32x16_bf16 v[0:15], v[132:135], v[170:173], v[0:15]
	v_mfma_f32_32x32x16_bf16 v[16:31], v[132:135], v[218:221], v[16:31]
	v_mfma_f32_32x32x16_bf16 v[0:15], v[128:131], v[174:177], v[0:15]
	v_mfma_f32_32x32x16_bf16 v[16:31], v[128:131], v[222:225], v[16:31]
	s_barrier
	s_nop 1
	v_max3_f32 v128, v64, v65, v66
	v_max3_f32 v129, v49, v50, v51
	v_max3_f32 v128, v128, v67, v68
	v_max3_f32 v129, v129, v52, v53
	v_max3_f32 v128, v128, v69, v70
	v_max3_f32 v129, v129, v54, v55
	v_max3_f32 v128, v128, v71, v72
	v_max3_f32 v129, v129, v56, v57
	v_max3_f32 v128, v128, v73, v74
	v_max3_f32 v129, v129, v58, v59
	v_max3_f32 v128, v128, v75, v76
	v_max3_f32 v129, v129, v60, v61
	v_max3_f32 v128, v128, v77, v78
	v_max3_f32 v129, v129, v62, v63
	v_max3_f32 v128, v128, v79, v48
	v_max_f32_e32 v128, v128, v129
	v_mov_b32_e32 v129, v128
	s_nop 1
	v_permlane32_swap_b32_e32 v128, v129
	v_max_f32_e32 v128, v128, v129
	v_cmp_ge_f32_e32 vcc, s83, v128
	v_mov_b32_e32 v161, 1.0
	s_cmp_eq_u64 vcc, exec
	s_cbranch_scc1 .LBB0_1241
	s_branch .LBB0_1245
